# v120 plus hand-written hg_pre scaled-operand pass (unrolled, LDS reads ahead, immediate-offset addresses, cvt_pk rounding, wave-uniform branches for the k~ parts)
# speedup vs baseline: 1.0058x; 1.0015x over previous
; __device__ __forceinline__ float bf2f(bfu h) { return __uint_as_float(((unsigned)h) << 16); }
; __device__ __forceinline__ int fragA_128(int r, int k) { return ((r >> 4) * 4 + (k >> 5)) * 512 + ((k >> 3) & 3) * 128 + (r & 15) * 8 + (k & 7); }
; __device__ void hg_pre_item(const Params& p, int L, int idx) {
;     ...
;   { const int d = tid & 127, rg = tid >> 7;
;     const float rown = (rg == 0) ? 0.f : bs[(16 * rg - 1) * 132 + d];
;     const float r1 = bs[15 * 132 + d], r2 = bs[31 * 132 + d], r3 = bs[47 * 132 + d];
;     for (int r = rg * 16; r < rg * 16 + 16; ++r) {
;       const float bb = bs[r * 132 + d];
;       const float qv = bf2f(qb[r * 136 + d]), kv = bf2f(kb[r * 136 + d]);
;       qt[r * 136 + d] = f2bf(qv * __builtin_amdgcn_exp2f(bb - rown));
;       { const int Lq = fragA_128(r, d); buf[(R0 + (Lq >> 7)) * 4608 + 1536 + h * 128 + (Lq & 127)] = f2bf(qv * __builtin_amdgcn_exp2f(bb)); }
;       if (rg < 1) kt[(0 + r) * 136 + d] = f2bf(kv * __builtin_amdgcn_exp2f(r1 - bb));
;       if (rg < 2) kt[(16 + r) * 136 + d] = f2bf(kv * __builtin_amdgcn_exp2f(r2 - bb));
;       if (rg < 3) kt[(48 + r) * 136 + d] = f2bf(kv * __builtin_amdgcn_exp2f(r3 - bb));
.LBB0_45:
	s_or_b64 exec, exec, s[0:1]
	v_cmp_lt_u32_e64 s[0:1], s24, v18
	v_mov_b32_e32 v9, 0
	v_lshlrev_b32_e32 v15, 2, v4
	s_waitcnt lgkmcnt(0)
	s_barrier
	v_mov_b32_e32 v240, s44
	v_lshrrev_b32_e32 v241, 8, v240
	v_add_u32_e32 v241, 1, v241
	v_min_u32_e32 v241, 7, v241
	v_and_b32_e32 v242, 63, v240
	v_lshlrev_b32_e32 v241, 12, v241
	v_lshl_or_b32 v241, v242, 6, v241
	v_mbcnt_lo_u32_b32 v243, -1, 0
	v_mbcnt_hi_u32_b32 v243, -1, v243
	v_or_b32_e32 v243, s33, v243
	v_lshrrev_b32_e32 v242, 3, v243
	v_and_b32_e32 v244, 7, v243
	v_min_u32_e32 v244, 5, v244
	v_add_u32_e32 v241, v241, v242
	v_mul_u32_u24_e32 v241, 0x2400, v241
	v_lshrrev_b32_e32 v245, 1, v244
	v_lshlrev_b32_e32 v245, 10, v245
	v_and_b32_e32 v244, 1, v244
	v_lshl_or_b32 v245, v244, 7, v245
	v_bfe_u32 v244, v240, 6, 2
	v_lshl_or_b32 v245, v244, 8, v245
	v_add_u32_e32 v245, 0xc00, v245
	v_add_u32_e32 v241, v241, v245
	global_load_dword v247, v241, s[16:17]
	s_and_saveexec_b64 s[12:13], s[0:1]
	v_add_u32_e32 v6, v20, v8
	s_movk_i32 s0, 0xfdf0
	v_add3_u32 v6, v6, v15, s0
	ds_read_b32 v9, v6
	s_or_b64 exec, exec, s[12:13]
	v_add_u32_e32 v6, 0xf0, v0
	ds_read2st64_b32 v[6:7], v6 offset0:30 offset1:63
	ds_read_b32 v11, v0 offset:24816
	v_lshlrev_b32_e32 v0, 4, v4
	s_movk_i32 s2, 0x1100
	v_and_b32_e32 v13, 0x180, v0
	v_mul_lo_u32 v0, v19, s2
	s_add_u32 s12, s16, s26
	v_lshl_or_b32 v0, v4, 1, v0
	v_lshrrev_b32_e32 v12, 5, v4
	v_and_b32_e32 v10, 7, v18
	v_cmp_gt_i32_e64 s[0:1], 1, v19
	v_cmp_gt_i32_e64 s[38:39], 2, v19
	v_cmp_gt_i32_e64 s[40:41], 3, v19
	s_addc_u32 s13, s17, 0
	v_lshlrev_b32_e32 v14, 7, v19
	v_add_u32_e32 v4, 0, v0
	v_add3_u32 v8, v8, v15, 0
	v_add_u32_e32 v112, v8, v5
	v_add_u32_e32 v113, v4, v5
	v_add_u32_e32 v114, 0x15400, v113
	v_add_u32_e32 v115, 0x19800, v113
	v_lshrrev_b32_e32 v116, 2, v2
	v_and_b32_e32 v116, 0x7ffffc, v116
	v_or_b32_e32 v116, v116, v12
	v_lshl_or_b32 v116, v116, 9, v13
	v_ashrrev_i32_e32 v116, 7, v116
	v_mov_b32_e32 v117, 0
	v_lshl_add_u64 v[116:117], s[46:47], 0, v[116:117]
	v_mov_b64_e32 v[118:119], s[12:13]
	v_mad_u64_u32 v[118:119], s[14:15], v116, s89, v[118:119]
	v_mad_u32_u24 v119, v117, s89, v119
	v_lshlrev_b32_e32 v120, 1, v10
	v_mov_b32_e32 v121, 0
	v_lshl_add_u64 v[118:119], v[118:119], 0, v[120:121]
	s_lshr_b32 s2, s33, 7
	ds_read_b32 v122, v112
	ds_read_u16 v138, v113 offset:33792
	ds_read_u16 v154, v113 offset:51200
	ds_read_b32 v123, v112 offset:528
	ds_read_u16 v139, v113 offset:34064
	ds_read_u16 v155, v113 offset:51472
	ds_read_b32 v124, v112 offset:1056
	ds_read_u16 v140, v113 offset:34336
	ds_read_u16 v156, v113 offset:51744
	ds_read_b32 v125, v112 offset:1584
	ds_read_u16 v141, v113 offset:34608
	ds_read_u16 v157, v113 offset:52016
	s_waitcnt lgkmcnt(6)
	v_sub_f32_e32 v170, v122, v9
	v_exp_f32_e32 v170, v170
	v_exp_f32_e32 v171, v122
	v_lshlrev_b32_e32 v138, 16, v138
	v_lshlrev_b32_e32 v154, 16, v154
	v_mul_f32_e32 v170, v170, v138
	v_mul_f32_e32 v171, v171, v138
	v_cvt_pk_bf16_f32 v170, v170, v170
	v_cvt_pk_bf16_f32 v171, v171, v171
	ds_write_b16 v114, v170
	global_store_short v[118:119], v171, off offset:3072
	v_sub_f32_e32 v170, v123, v9
	v_exp_f32_e32 v170, v170
	v_exp_f32_e32 v171, v123
	v_lshlrev_b32_e32 v139, 16, v139
	v_lshlrev_b32_e32 v155, 16, v155
	v_mul_f32_e32 v170, v170, v139
	v_mul_f32_e32 v171, v171, v139
	v_cvt_pk_bf16_f32 v170, v170, v170
	v_cvt_pk_bf16_f32 v171, v171, v171
	ds_write_b16 v114, v170 offset:272
	global_store_short v[118:119], v171, off offset:3088
	ds_read_b32 v126, v112 offset:2112
	ds_read_u16 v142, v113 offset:34880
	ds_read_u16 v158, v113 offset:52288
	ds_read_b32 v127, v112 offset:2640
	ds_read_u16 v143, v113 offset:35152
	ds_read_u16 v159, v113 offset:52560
	s_waitcnt lgkmcnt(6)
	v_sub_f32_e32 v170, v124, v9
	v_exp_f32_e32 v170, v170
	v_exp_f32_e32 v171, v124
	v_lshlrev_b32_e32 v140, 16, v140
	v_lshlrev_b32_e32 v156, 16, v156
	v_mul_f32_e32 v170, v170, v140
	v_mul_f32_e32 v171, v171, v140
	v_cvt_pk_bf16_f32 v170, v170, v170
	v_cvt_pk_bf16_f32 v171, v171, v171
	ds_write_b16 v114, v170 offset:544
	global_store_short v[118:119], v171, off offset:3104
	v_sub_f32_e32 v170, v125, v9
	v_exp_f32_e32 v170, v170
	v_exp_f32_e32 v171, v125
	v_lshlrev_b32_e32 v141, 16, v141
	v_lshlrev_b32_e32 v157, 16, v157
	v_mul_f32_e32 v170, v170, v141
	v_mul_f32_e32 v171, v171, v141
	v_cvt_pk_bf16_f32 v170, v170, v170
	v_cvt_pk_bf16_f32 v171, v171, v171
	ds_write_b16 v114, v170 offset:816
	global_store_short v[118:119], v171, off offset:3120
	ds_read_b32 v128, v112 offset:3168
	ds_read_u16 v144, v113 offset:35424
	ds_read_u16 v160, v113 offset:52832
	ds_read_b32 v129, v112 offset:3696
	ds_read_u16 v145, v113 offset:35696
	ds_read_u16 v161, v113 offset:53104
	s_waitcnt lgkmcnt(6)
	v_sub_f32_e32 v170, v126, v9
	v_exp_f32_e32 v170, v170
	v_exp_f32_e32 v171, v126
	v_lshlrev_b32_e32 v142, 16, v142
	v_lshlrev_b32_e32 v158, 16, v158
	v_mul_f32_e32 v170, v170, v142
	v_mul_f32_e32 v171, v171, v142
	v_cvt_pk_bf16_f32 v170, v170, v170
	v_cvt_pk_bf16_f32 v171, v171, v171
	ds_write_b16 v114, v170 offset:1088
	global_store_short v[118:119], v171, off offset:3136
	v_sub_f32_e32 v170, v127, v9
	v_exp_f32_e32 v170, v170
	v_exp_f32_e32 v171, v127
	v_lshlrev_b32_e32 v143, 16, v143
	v_lshlrev_b32_e32 v159, 16, v159
	v_mul_f32_e32 v170, v170, v143
	v_mul_f32_e32 v171, v171, v143
	v_cvt_pk_bf16_f32 v170, v170, v170
	v_cvt_pk_bf16_f32 v171, v171, v171
	ds_write_b16 v114, v170 offset:1360
	global_store_short v[118:119], v171, off offset:3152
	ds_read_b32 v130, v112 offset:4224
	ds_read_u16 v146, v113 offset:35968
	ds_read_u16 v162, v113 offset:53376
	ds_read_b32 v131, v112 offset:4752
	ds_read_u16 v147, v113 offset:36240
	ds_read_u16 v163, v113 offset:53648
	s_waitcnt lgkmcnt(6)
; __device__ __forceinline__ float bf2f(bfu h) { return __uint_as_float(((unsigned)h) << 16); }
; __device__ __forceinline__ int fragA_128(int r, int k) { return ((r >> 4) * 4 + (k >> 5)) * 512 + ((k >> 3) & 3) * 128 + (r & 15) * 8 + (k & 7); }
; __device__ void hg_pre_item(const Params& p, int L, int idx) {
;     ...
;     for (int r = rg * 16; r < rg * 16 + 16; ++r) {
;       const float bb = bs[r * 132 + d];
;       const float qv = bf2f(qb[r * 136 + d]), kv = bf2f(kb[r * 136 + d]);
;       qt[r * 136 + d] = f2bf(qv * __builtin_amdgcn_exp2f(bb - rown));
;       { const int Lq = fragA_128(r, d); buf[(R0 + (Lq >> 7)) * 4608 + 1536 + h * 128 + (Lq & 127)] = f2bf(qv * __builtin_amdgcn_exp2f(bb)); }
;       if (rg < 1) kt[(0 + r) * 136 + d] = f2bf(kv * __builtin_amdgcn_exp2f(r1 - bb));
;       if (rg < 2) kt[(16 + r) * 136 + d] = f2bf(kv * __builtin_amdgcn_exp2f(r2 - bb));
;       if (rg < 3) kt[(48 + r) * 136 + d] = f2bf(kv * __builtin_amdgcn_exp2f(r3 - bb));
	v_sub_f32_e32 v170, v128, v9
	v_exp_f32_e32 v170, v170
	v_exp_f32_e32 v171, v128
	v_lshlrev_b32_e32 v144, 16, v144
	v_lshlrev_b32_e32 v160, 16, v160
	v_mul_f32_e32 v170, v170, v144
	v_mul_f32_e32 v171, v171, v144
	v_cvt_pk_bf16_f32 v170, v170, v170
	v_cvt_pk_bf16_f32 v171, v171, v171
	ds_write_b16 v114, v170 offset:1632
	global_store_short v[118:119], v171, off offset:3168
	v_sub_f32_e32 v170, v129, v9
	v_exp_f32_e32 v170, v170
	v_exp_f32_e32 v171, v129
	v_lshlrev_b32_e32 v145, 16, v145
	v_lshlrev_b32_e32 v161, 16, v161
	v_mul_f32_e32 v170, v170, v145
	v_mul_f32_e32 v171, v171, v145
	v_cvt_pk_bf16_f32 v170, v170, v170
	v_cvt_pk_bf16_f32 v171, v171, v171
	ds_write_b16 v114, v170 offset:1904
	global_store_short v[118:119], v171, off offset:3184
	ds_read_b32 v132, v112 offset:5280
	ds_read_u16 v148, v113 offset:36512
	ds_read_u16 v164, v113 offset:53920
	ds_read_b32 v133, v112 offset:5808
	ds_read_u16 v149, v113 offset:36784
	ds_read_u16 v165, v113 offset:54192
	s_waitcnt lgkmcnt(6)
	v_sub_f32_e32 v170, v130, v9
	v_exp_f32_e32 v170, v170
	v_exp_f32_e32 v171, v130
	v_lshlrev_b32_e32 v146, 16, v146
	v_lshlrev_b32_e32 v162, 16, v162
	v_mul_f32_e32 v170, v170, v146
	v_mul_f32_e32 v171, v171, v146
	v_cvt_pk_bf16_f32 v170, v170, v170
	v_cvt_pk_bf16_f32 v171, v171, v171
	ds_write_b16 v114, v170 offset:2176
	global_store_short v[118:119], v171, off offset:3200
	v_sub_f32_e32 v170, v131, v9
	v_exp_f32_e32 v170, v170
	v_exp_f32_e32 v171, v131
	v_lshlrev_b32_e32 v147, 16, v147
	v_lshlrev_b32_e32 v163, 16, v163
	v_mul_f32_e32 v170, v170, v147
	v_mul_f32_e32 v171, v171, v147
	v_cvt_pk_bf16_f32 v170, v170, v170
	v_cvt_pk_bf16_f32 v171, v171, v171
	ds_write_b16 v114, v170 offset:2448
	global_store_short v[118:119], v171, off offset:3216
	ds_read_b32 v134, v112 offset:6336
	ds_read_u16 v150, v113 offset:37056
	ds_read_u16 v166, v113 offset:54464
	ds_read_b32 v135, v112 offset:6864
	ds_read_u16 v151, v113 offset:37328
	ds_read_u16 v167, v113 offset:54736
	s_waitcnt lgkmcnt(6)
	v_sub_f32_e32 v170, v132, v9
	v_exp_f32_e32 v170, v170
	v_exp_f32_e32 v171, v132
	v_lshlrev_b32_e32 v148, 16, v148
	v_lshlrev_b32_e32 v164, 16, v164
	v_mul_f32_e32 v170, v170, v148
	v_mul_f32_e32 v171, v171, v148
	v_cvt_pk_bf16_f32 v170, v170, v170
	v_cvt_pk_bf16_f32 v171, v171, v171
	ds_write_b16 v114, v170 offset:2720
	global_store_short v[118:119], v171, off offset:3232
	v_sub_f32_e32 v170, v133, v9
	v_exp_f32_e32 v170, v170
	v_exp_f32_e32 v171, v133
	v_lshlrev_b32_e32 v149, 16, v149
	v_lshlrev_b32_e32 v165, 16, v165
	v_mul_f32_e32 v170, v170, v149
	v_mul_f32_e32 v171, v171, v149
	v_cvt_pk_bf16_f32 v170, v170, v170
	v_cvt_pk_bf16_f32 v171, v171, v171
	ds_write_b16 v114, v170 offset:2992
	global_store_short v[118:119], v171, off offset:3248
	ds_read_b32 v136, v112 offset:7392
	ds_read_u16 v152, v113 offset:37600
	ds_read_u16 v168, v113 offset:55008
	ds_read_b32 v137, v112 offset:7920
	ds_read_u16 v153, v113 offset:37872
	ds_read_u16 v169, v113 offset:55280
	s_waitcnt lgkmcnt(6)
	v_sub_f32_e32 v170, v134, v9
	v_exp_f32_e32 v170, v170
	v_exp_f32_e32 v171, v134
	v_lshlrev_b32_e32 v150, 16, v150
	v_lshlrev_b32_e32 v166, 16, v166
	v_mul_f32_e32 v170, v170, v150
	v_mul_f32_e32 v171, v171, v150
	v_cvt_pk_bf16_f32 v170, v170, v170
	v_cvt_pk_bf16_f32 v171, v171, v171
	ds_write_b16 v114, v170 offset:3264
	global_store_short v[118:119], v171, off offset:3264
	v_sub_f32_e32 v170, v135, v9
	v_exp_f32_e32 v170, v170
	v_exp_f32_e32 v171, v135
	v_lshlrev_b32_e32 v151, 16, v151
	v_lshlrev_b32_e32 v167, 16, v167
	v_mul_f32_e32 v170, v170, v151
	v_mul_f32_e32 v171, v171, v151
	v_cvt_pk_bf16_f32 v170, v170, v170
	v_cvt_pk_bf16_f32 v171, v171, v171
	ds_write_b16 v114, v170 offset:3536
	global_store_short v[118:119], v171, off offset:3280
	s_waitcnt lgkmcnt(0)
	v_sub_f32_e32 v170, v136, v9
	v_exp_f32_e32 v170, v170
	v_exp_f32_e32 v171, v136
	v_lshlrev_b32_e32 v152, 16, v152
	v_lshlrev_b32_e32 v168, 16, v168
	v_mul_f32_e32 v170, v170, v152
	v_mul_f32_e32 v171, v171, v152
	v_cvt_pk_bf16_f32 v170, v170, v170
	v_cvt_pk_bf16_f32 v171, v171, v171
	ds_write_b16 v114, v170 offset:3808
	global_store_short v[118:119], v171, off offset:3296
	v_sub_f32_e32 v170, v137, v9
	v_exp_f32_e32 v170, v170
	v_exp_f32_e32 v171, v137
	v_lshlrev_b32_e32 v153, 16, v153
	v_lshlrev_b32_e32 v169, 16, v169
	v_mul_f32_e32 v170, v170, v153
	v_mul_f32_e32 v171, v171, v153
	v_cvt_pk_bf16_f32 v170, v170, v170
	v_cvt_pk_bf16_f32 v171, v171, v171
	ds_write_b16 v114, v170 offset:4080
	global_store_short v[118:119], v171, off offset:3312
	s_cmp_lt_u32 s2, 1
	s_cbranch_scc0 .Lhgq_k0
; __device__ void hg_pre_item(const Params& p, int L, int idx) {
;     ...
;       if (rg < 1) kt[(0 + r) * 136 + d] = f2bf(kv * __builtin_amdgcn_exp2f(r1 - bb));
;       if (rg < 2) kt[(16 + r) * 136 + d] = f2bf(kv * __builtin_amdgcn_exp2f(r2 - bb));
;       if (rg < 3) kt[(48 + r) * 136 + d] = f2bf(kv * __builtin_amdgcn_exp2f(r3 - bb));
	v_sub_f32_e32 v170, v6, v122
	v_exp_f32_e32 v170, v170
	s_nop 0
	v_mul_f32_e32 v170, v170, v154
	v_cvt_pk_bf16_f32 v170, v170, v170
	ds_write_b16 v115, v170
	v_sub_f32_e32 v170, v6, v123
	v_exp_f32_e32 v170, v170
	s_nop 0
	v_mul_f32_e32 v170, v170, v155
	v_cvt_pk_bf16_f32 v170, v170, v170
	ds_write_b16 v115, v170 offset:272
	v_sub_f32_e32 v170, v6, v124
	v_exp_f32_e32 v170, v170
	s_nop 0
	v_mul_f32_e32 v170, v170, v156
	v_cvt_pk_bf16_f32 v170, v170, v170
	ds_write_b16 v115, v170 offset:544
	v_sub_f32_e32 v170, v6, v125
	v_exp_f32_e32 v170, v170
	s_nop 0
	v_mul_f32_e32 v170, v170, v157
	v_cvt_pk_bf16_f32 v170, v170, v170
	ds_write_b16 v115, v170 offset:816
	v_sub_f32_e32 v170, v6, v126
	v_exp_f32_e32 v170, v170
	s_nop 0
	v_mul_f32_e32 v170, v170, v158
	v_cvt_pk_bf16_f32 v170, v170, v170
	ds_write_b16 v115, v170 offset:1088
	v_sub_f32_e32 v170, v6, v127
	v_exp_f32_e32 v170, v170
	s_nop 0
	v_mul_f32_e32 v170, v170, v159
	v_cvt_pk_bf16_f32 v170, v170, v170
	ds_write_b16 v115, v170 offset:1360
	v_sub_f32_e32 v170, v6, v128
	v_exp_f32_e32 v170, v170
	s_nop 0
	v_mul_f32_e32 v170, v170, v160
	v_cvt_pk_bf16_f32 v170, v170, v170
	ds_write_b16 v115, v170 offset:1632
	v_sub_f32_e32 v170, v6, v129
	v_exp_f32_e32 v170, v170
	s_nop 0
	v_mul_f32_e32 v170, v170, v161
	v_cvt_pk_bf16_f32 v170, v170, v170
	ds_write_b16 v115, v170 offset:1904
	v_sub_f32_e32 v170, v6, v130
	v_exp_f32_e32 v170, v170
	s_nop 0
	v_mul_f32_e32 v170, v170, v162
	v_cvt_pk_bf16_f32 v170, v170, v170
	ds_write_b16 v115, v170 offset:2176
	v_sub_f32_e32 v170, v6, v131
	v_exp_f32_e32 v170, v170
	s_nop 0
	v_mul_f32_e32 v170, v170, v163
	v_cvt_pk_bf16_f32 v170, v170, v170
	ds_write_b16 v115, v170 offset:2448
	v_sub_f32_e32 v170, v6, v132
	v_exp_f32_e32 v170, v170
	s_nop 0
	v_mul_f32_e32 v170, v170, v164
	v_cvt_pk_bf16_f32 v170, v170, v170
	ds_write_b16 v115, v170 offset:2720
	v_sub_f32_e32 v170, v6, v133
	v_exp_f32_e32 v170, v170
	s_nop 0
	v_mul_f32_e32 v170, v170, v165
	v_cvt_pk_bf16_f32 v170, v170, v170
	ds_write_b16 v115, v170 offset:2992
	v_sub_f32_e32 v170, v6, v134
	v_exp_f32_e32 v170, v170
	s_nop 0
	v_mul_f32_e32 v170, v170, v166
	v_cvt_pk_bf16_f32 v170, v170, v170
	ds_write_b16 v115, v170 offset:3264
	v_sub_f32_e32 v170, v6, v135
	v_exp_f32_e32 v170, v170
	s_nop 0
	v_mul_f32_e32 v170, v170, v167
	v_cvt_pk_bf16_f32 v170, v170, v170
	ds_write_b16 v115, v170 offset:3536
	v_sub_f32_e32 v170, v6, v136
	v_exp_f32_e32 v170, v170
	s_nop 0
	v_mul_f32_e32 v170, v170, v168
	v_cvt_pk_bf16_f32 v170, v170, v170
	ds_write_b16 v115, v170 offset:3808
	v_sub_f32_e32 v170, v6, v137
	v_exp_f32_e32 v170, v170
	s_nop 0
	v_mul_f32_e32 v170, v170, v169
	v_cvt_pk_bf16_f32 v170, v170, v170
	ds_write_b16 v115, v170 offset:4080
.Lhgq_k0:
	s_cmp_lt_u32 s2, 2
	s_cbranch_scc0 .Lhgq_k1
	v_sub_f32_e32 v170, v7, v122
	v_exp_f32_e32 v170, v170
	s_nop 0
	v_mul_f32_e32 v170, v170, v154
	v_cvt_pk_bf16_f32 v170, v170, v170
	ds_write_b16 v115, v170 offset:4352
	v_sub_f32_e32 v170, v7, v123
	v_exp_f32_e32 v170, v170
	s_nop 0
	v_mul_f32_e32 v170, v170, v155
	v_cvt_pk_bf16_f32 v170, v170, v170
	ds_write_b16 v115, v170 offset:4624
	v_sub_f32_e32 v170, v7, v124
	v_exp_f32_e32 v170, v170
	s_nop 0
	v_mul_f32_e32 v170, v170, v156
	v_cvt_pk_bf16_f32 v170, v170, v170
	ds_write_b16 v115, v170 offset:4896
	v_sub_f32_e32 v170, v7, v125
	v_exp_f32_e32 v170, v170
	s_nop 0
	v_mul_f32_e32 v170, v170, v157
	v_cvt_pk_bf16_f32 v170, v170, v170
	ds_write_b16 v115, v170 offset:5168
	v_sub_f32_e32 v170, v7, v126
	v_exp_f32_e32 v170, v170
	s_nop 0
	v_mul_f32_e32 v170, v170, v158
	v_cvt_pk_bf16_f32 v170, v170, v170
	ds_write_b16 v115, v170 offset:5440
	v_sub_f32_e32 v170, v7, v127
	v_exp_f32_e32 v170, v170
	s_nop 0
	v_mul_f32_e32 v170, v170, v159
	v_cvt_pk_bf16_f32 v170, v170, v170
	ds_write_b16 v115, v170 offset:5712
	v_sub_f32_e32 v170, v7, v128
	v_exp_f32_e32 v170, v170
	s_nop 0
	v_mul_f32_e32 v170, v170, v160
	v_cvt_pk_bf16_f32 v170, v170, v170
	ds_write_b16 v115, v170 offset:5984
	v_sub_f32_e32 v170, v7, v129
	v_exp_f32_e32 v170, v170
	s_nop 0
	v_mul_f32_e32 v170, v170, v161
	v_cvt_pk_bf16_f32 v170, v170, v170
	ds_write_b16 v115, v170 offset:6256
	v_sub_f32_e32 v170, v7, v130
	v_exp_f32_e32 v170, v170
	s_nop 0
	v_mul_f32_e32 v170, v170, v162
	v_cvt_pk_bf16_f32 v170, v170, v170
	ds_write_b16 v115, v170 offset:6528
	v_sub_f32_e32 v170, v7, v131
	v_exp_f32_e32 v170, v170
	s_nop 0
	v_mul_f32_e32 v170, v170, v163
	v_cvt_pk_bf16_f32 v170, v170, v170
	ds_write_b16 v115, v170 offset:6800
	v_sub_f32_e32 v170, v7, v132
	v_exp_f32_e32 v170, v170
	s_nop 0
	v_mul_f32_e32 v170, v170, v164
	v_cvt_pk_bf16_f32 v170, v170, v170
	ds_write_b16 v115, v170 offset:7072
	v_sub_f32_e32 v170, v7, v133
	v_exp_f32_e32 v170, v170
	s_nop 0
	v_mul_f32_e32 v170, v170, v165
	v_cvt_pk_bf16_f32 v170, v170, v170
	ds_write_b16 v115, v170 offset:7344
	v_sub_f32_e32 v170, v7, v134
	v_exp_f32_e32 v170, v170
	s_nop 0
	v_mul_f32_e32 v170, v170, v166
	v_cvt_pk_bf16_f32 v170, v170, v170
	ds_write_b16 v115, v170 offset:7616
	v_sub_f32_e32 v170, v7, v135
	v_exp_f32_e32 v170, v170
	s_nop 0
	v_mul_f32_e32 v170, v170, v167
	v_cvt_pk_bf16_f32 v170, v170, v170
	ds_write_b16 v115, v170 offset:7888
	v_sub_f32_e32 v170, v7, v136
	v_exp_f32_e32 v170, v170
	s_nop 0
	v_mul_f32_e32 v170, v170, v168
	v_cvt_pk_bf16_f32 v170, v170, v170
	ds_write_b16 v115, v170 offset:8160
	v_sub_f32_e32 v170, v7, v137
	v_exp_f32_e32 v170, v170
	s_nop 0
	v_mul_f32_e32 v170, v170, v169
	v_cvt_pk_bf16_f32 v170, v170, v170
	ds_write_b16 v115, v170 offset:8432
; __device__ void hg_pre_item(const Params& p, int L, int idx) {
;     ...
;       if (rg < 1) kt[(0 + r) * 136 + d] = f2bf(kv * __builtin_amdgcn_exp2f(r1 - bb));
;       if (rg < 2) kt[(16 + r) * 136 + d] = f2bf(kv * __builtin_amdgcn_exp2f(r2 - bb));
;       if (rg < 3) kt[(48 + r) * 136 + d] = f2bf(kv * __builtin_amdgcn_exp2f(r3 - bb));
;     }
;     if (tid < 128) misc[MF_EB + (long)idx * 128 + tid] = __builtin_amdgcn_exp2f(bs[63 * 132 + tid]);
.Lhgq_k1:
	s_cmp_lt_u32 s2, 3
	s_cbranch_scc0 .Lhgq_k2
	v_sub_f32_e32 v170, v11, v122
	v_exp_f32_e32 v170, v170
	s_nop 0
	v_mul_f32_e32 v170, v170, v154
	v_cvt_pk_bf16_f32 v170, v170, v170
	ds_write_b16 v115, v170 offset:13056
	v_sub_f32_e32 v170, v11, v123
	v_exp_f32_e32 v170, v170
	s_nop 0
	v_mul_f32_e32 v170, v170, v155
	v_cvt_pk_bf16_f32 v170, v170, v170
	ds_write_b16 v115, v170 offset:13328
	v_sub_f32_e32 v170, v11, v124
	v_exp_f32_e32 v170, v170
	s_nop 0
	v_mul_f32_e32 v170, v170, v156
	v_cvt_pk_bf16_f32 v170, v170, v170
	ds_write_b16 v115, v170 offset:13600
	v_sub_f32_e32 v170, v11, v125
	v_exp_f32_e32 v170, v170
	s_nop 0
	v_mul_f32_e32 v170, v170, v157
	v_cvt_pk_bf16_f32 v170, v170, v170
	ds_write_b16 v115, v170 offset:13872
	v_sub_f32_e32 v170, v11, v126
	v_exp_f32_e32 v170, v170
	s_nop 0
	v_mul_f32_e32 v170, v170, v158
	v_cvt_pk_bf16_f32 v170, v170, v170
	ds_write_b16 v115, v170 offset:14144
	v_sub_f32_e32 v170, v11, v127
	v_exp_f32_e32 v170, v170
	s_nop 0
	v_mul_f32_e32 v170, v170, v159
	v_cvt_pk_bf16_f32 v170, v170, v170
	ds_write_b16 v115, v170 offset:14416
	v_sub_f32_e32 v170, v11, v128
	v_exp_f32_e32 v170, v170
	s_nop 0
	v_mul_f32_e32 v170, v170, v160
	v_cvt_pk_bf16_f32 v170, v170, v170
	ds_write_b16 v115, v170 offset:14688
	v_sub_f32_e32 v170, v11, v129
	v_exp_f32_e32 v170, v170
	s_nop 0
	v_mul_f32_e32 v170, v170, v161
	v_cvt_pk_bf16_f32 v170, v170, v170
	ds_write_b16 v115, v170 offset:14960
	v_sub_f32_e32 v170, v11, v130
	v_exp_f32_e32 v170, v170
	s_nop 0
	v_mul_f32_e32 v170, v170, v162
	v_cvt_pk_bf16_f32 v170, v170, v170
	ds_write_b16 v115, v170 offset:15232
	v_sub_f32_e32 v170, v11, v131
	v_exp_f32_e32 v170, v170
	s_nop 0
	v_mul_f32_e32 v170, v170, v163
	v_cvt_pk_bf16_f32 v170, v170, v170
	ds_write_b16 v115, v170 offset:15504
	v_sub_f32_e32 v170, v11, v132
	v_exp_f32_e32 v170, v170
	s_nop 0
	v_mul_f32_e32 v170, v170, v164
	v_cvt_pk_bf16_f32 v170, v170, v170
	ds_write_b16 v115, v170 offset:15776
	v_sub_f32_e32 v170, v11, v133
	v_exp_f32_e32 v170, v170
	s_nop 0
	v_mul_f32_e32 v170, v170, v165
	v_cvt_pk_bf16_f32 v170, v170, v170
	ds_write_b16 v115, v170 offset:16048
	v_sub_f32_e32 v170, v11, v134
	v_exp_f32_e32 v170, v170
	s_nop 0
	v_mul_f32_e32 v170, v170, v166
	v_cvt_pk_bf16_f32 v170, v170, v170
	ds_write_b16 v115, v170 offset:16320
	v_sub_f32_e32 v170, v11, v135
	v_exp_f32_e32 v170, v170
	s_nop 0
	v_mul_f32_e32 v170, v170, v167
	v_cvt_pk_bf16_f32 v170, v170, v170
	ds_write_b16 v115, v170 offset:16592
	v_sub_f32_e32 v170, v11, v136
	v_exp_f32_e32 v170, v170
	s_nop 0
	v_mul_f32_e32 v170, v170, v168
	v_cvt_pk_bf16_f32 v170, v170, v170
	ds_write_b16 v115, v170 offset:16864
	v_sub_f32_e32 v170, v11, v137
	v_exp_f32_e32 v170, v170
	s_nop 0
	v_mul_f32_e32 v170, v170, v169
	v_cvt_pk_bf16_f32 v170, v170, v170
	ds_write_b16 v115, v170 offset:17136
.Lhgq_k2:
.LBB0_55:
	s_and_saveexec_b64 s[0:1], vcc
	s_cbranch_execz .LBB0_57
	ds_read_b32 v0, v3 offset:33264
	s_ashr_i32 s45, s44, 31
	s_lshl_b64 s[2:3], s[44:45], 9
	v_readlane_b32 s12, v254, 48
	v_readlane_b32 s13, v254, 49
	s_add_u32 s2, s12, s2
	s_addc_u32 s3, s13, s3
	v_ashrrev_i32_e32 v19, 31, v18
	s_waitcnt lgkmcnt(0)
	v_exp_f32_e32 v0, v0
	v_lshl_add_u64 v[2:3], v[18:19], 2, s[2:3]
	v_add_co_u32_e32 v2, vcc, 0x233000, v2
	s_nop 1
	v_addc_co_u32_e32 v3, vcc, 0, v3, vcc
	global_store_dword v[2:3], v0, off
